# grid barrier steady state hand-written: XCD arrive, leader wbl2 + one top-level add, all blocks poll top-level count (two hops fewer)
# speedup vs baseline: 1.0181x; 1.0064x over previous
; DEV unsigned xb_ld(unsigned* p)              { return __hip_atomic_load(p, __ATOMIC_RELAXED, __HIP_MEMORY_SCOPE_AGENT); }
; DEV unsigned xb_add(unsigned* p, unsigned v) { return __hip_atomic_fetch_add(p, v, __ATOMIC_RELAXED, __HIP_MEMORY_SCOPE_AGENT); }
; #define XB_SPIN(cond, bar) do { unsigned _sp = 0; while (cond) { __builtin_amdgcn_s_sleep(1); \
;     if ((++_sp & 255u) == 0u) { if (xb_ld(&(bar)[XB_TMO])) break; if (_sp > XB_SPIN_CAP) { atomicAdd(&(bar)[XB_TMO], 1u); break; } } } } while (0)
; DEV void xcd_barrier(const XcdBarrier& b) {
;   asm volatile("s_waitcnt vmcnt(0)" ::: "memory");
;   __syncthreads();
;   if (threadIdx.x == 0) {
;     unsigned* bar = b.bar;
;     __builtin_amdgcn_s_waitcnt(0);
;     unsigned nloc = b.st[0], nx = b.st[1];
;     if (nloc == 0u) { xcd_barrier_complete(bar, b.x, nloc, nx); b.st[0] = nloc; b.st[1] = nx; }
;     const unsigned old = xb_add(&bar[XB_XSUB(b.x)], 1u);
;     const unsigned gen = old / nloc;
;     if (old + 1u == (gen + 1u) * nloc) {
;       __builtin_amdgcn_fence(__ATOMIC_RELEASE, "agent");
;       asm volatile("s_waitcnt vmcnt(0)" ::: "memory");
;       const unsigned og = xb_add(&bar[XB_TOP], 1u);
;       const unsigned tg = og / nx;
;       if (og + 1u == (tg + 1u) * nx) xb_add(&bar[XB_TOPGEN], 1u);
;       else XB_SPIN(xb_ld(&bar[XB_TOPGEN]) == tg, bar);
;       __builtin_amdgcn_fence(__ATOMIC_ACQUIRE, "agent");
;       xb_add(&bar[XB_XGEN(b.x)], 1u);
;       asm volatile("s_waitcnt vmcnt(0)" ::: "memory");
;     } else {
;       XB_SPIN(xb_ld(&bar[XB_XGEN(b.x)]) == gen, bar);
;       __builtin_amdgcn_fence(__ATOMIC_ACQUIRE, "agent");
;       asm volatile("s_waitcnt vmcnt(0)" ::: "memory");
;     }
;   }
;   __syncthreads();
.LBB0_27:
	s_sub_i32 s6, s21, s28
	v_readlane_b32 s4, v249, 25
	v_readlane_b32 s5, v249, 26
	v_readlane_b32 s8, v249, 31
	v_readlane_b32 s9, v249, 32
	v_mov_b32_e32 v3, 1
	s_waitcnt lgkmcnt(0)
	v_mul_lo_u32 v1, v0, s6
	v_mul_lo_u32 v4, v2, s6
	s_mov_b32 s12, 0
	s_nop 1
	global_atomic_add v3, v169, v3, s[4:5] sc0
	s_waitcnt vmcnt(0)
	v_add_u32_e32 v3, 1, v3
	v_cmp_eq_u32_e32 vcc, v3, v4
	s_cbranch_vccz .Lbar_poll
	buffer_wbl2 sc1
	s_waitcnt vmcnt(0)
	global_atomic_add v169, v200, s[8:9]
.Lbar_poll:
	global_load_dword v5, v169, s[8:9] sc1
	s_add_i32 s12, s12, 1
	s_waitcnt vmcnt(0)
	v_cmp_ge_u32_e32 vcc, v5, v1
	s_cbranch_vccnz .Lbar_done
	s_cmp_lt_u32 s12, 0x200000
	s_cbranch_scc0 .Lbar_done
	s_sleep 1
	s_branch .Lbar_poll
.Lbar_done:
	buffer_inv sc1
	s_waitcnt vmcnt(0)
